# attention write-out stores non-temporal (keep the item's K/V in L2), on stack21
# speedup vs baseline: 1.0047x; 1.0024x over previous
; #define LAS __attribute__((address_space(3)))
; __device__ __forceinline__ void attn_phase(const Args& A, LAS unsigned char* lds, int tid, int lane, int wave, int bx, int G) {
;     ...
;         {
;             bf16_t* Op = (bf16_t*)(A.ws + WS_O) + (size_t)(bh >> 4) * SEQ * 1024 + (bh & 15) * 64;
; #pragma unroll
;             for (int rd = 0; rd < 8; ++rd) { const int idx = rd * NTHR + tid, row = idx >> 3, ch = idx & 7;
;                 const u32x4 v = *(const LAS u32x4*)(lds + row * OB_STRIDE + ch * 16);
;                 *(u32x4*)(Op + (size_t)(pos0 + row) * 1024 + ch * 8) = v; }
;         }
.LBB0_430:
	v_readlane_b32 s2, v254, 59
	s_ashr_i32 s6, s2, 8
	s_ashr_i32 s7, s6, 31
	s_lshl_b64 s[6:7], s[6:7], 24
	v_readlane_b32 s3, v253, 60
	s_add_u32 s3, s3, s6
	v_readlane_b32 s6, v253, 61
	s_addc_u32 s7, s6, s7
	s_lshl_b32 s6, s24, 7
	s_and_b32 s6, s6, 0x780
	ds_read_b128 v[0:3], v203
	s_add_u32 s6, s3, s6
	v_add_u32_e32 v6, s10, v175
	s_addc_u32 s7, s7, 0
	v_mov_b32_e32 v159, v177
	v_ashrrev_i32_e32 v7, 31, v6
	v_lshl_add_u64 v[4:5], s[6:7], 0, v[158:159]
	v_lshlrev_b64 v[6:7], 11, v[6:7]
	v_lshl_add_u64 v[6:7], v[4:5], 0, v[6:7]
	s_waitcnt lgkmcnt(0)
	global_store_dwordx4 v[6:7], v[0:3], off nt
	ds_read_b128 v[0:3], v204
	v_add_u32_e32 v6, s10, v194
	v_ashrrev_i32_e32 v7, 31, v6
	v_lshlrev_b64 v[6:7], 11, v[6:7]
	v_lshl_add_u64 v[6:7], v[4:5], 0, v[6:7]
	s_waitcnt lgkmcnt(0)
	global_store_dwordx4 v[6:7], v[0:3], off nt
	ds_read_b128 v[0:3], v205
	v_add_u32_e32 v6, s10, v195
	v_ashrrev_i32_e32 v7, 31, v6
	v_lshlrev_b64 v[6:7], 11, v[6:7]
	v_lshl_add_u64 v[6:7], v[4:5], 0, v[6:7]
	s_waitcnt lgkmcnt(0)
	global_store_dwordx4 v[6:7], v[0:3], off nt
	ds_read_b128 v[0:3], v206
	v_add_u32_e32 v6, s10, v196
	v_ashrrev_i32_e32 v7, 31, v6
	v_lshlrev_b64 v[6:7], 11, v[6:7]
	v_lshl_add_u64 v[6:7], v[4:5], 0, v[6:7]
	s_waitcnt lgkmcnt(0)
	global_store_dwordx4 v[6:7], v[0:3], off nt
	ds_read_b128 v[0:3], v207
	v_add_u32_e32 v6, s10, v197
	v_ashrrev_i32_e32 v7, 31, v6
	v_lshlrev_b64 v[6:7], 11, v[6:7]
	v_lshl_add_u64 v[6:7], v[4:5], 0, v[6:7]
	s_waitcnt lgkmcnt(0)
	global_store_dwordx4 v[6:7], v[0:3], off nt
	ds_read_b128 v[0:3], v208
	v_add_u32_e32 v6, s10, v198
	v_ashrrev_i32_e32 v7, 31, v6
	v_lshlrev_b64 v[6:7], 11, v[6:7]
	v_lshl_add_u64 v[6:7], v[4:5], 0, v[6:7]
	s_waitcnt lgkmcnt(0)
	global_store_dwordx4 v[6:7], v[0:3], off nt
	ds_read_b128 v[0:3], v209
	v_add_u32_e32 v6, s10, v199
	v_ashrrev_i32_e32 v7, 31, v6
	v_lshlrev_b64 v[6:7], 11, v[6:7]
	v_lshl_add_u64 v[6:7], v[4:5], 0, v[6:7]
	s_waitcnt lgkmcnt(0)
	global_store_dwordx4 v[6:7], v[0:3], off nt
	ds_read_b128 v[0:3], v210
	v_add_u32_e32 v6, s10, v200
	v_ashrrev_i32_e32 v7, 31, v6
	v_lshlrev_b64 v[6:7], 11, v[6:7]
	v_lshl_add_u64 v[4:5], v[4:5], 0, v[6:7]
	s_mov_b64 s[6:7], 0
	v_readlane_b32 s2, v254, 62
	s_waitcnt lgkmcnt(0)
	global_store_dwordx4 v[4:5], v[0:3], off nt
	s_barrier
	s_branch .LBB0_374
